# v31 + group-norm/gate phase: next token's 8 row loads prefetched into spare VGPRs and copied at loop top (no in-loop load-wait ladder)
# speedup vs baseline: 1.0028x; 1.0028x over previous
.LBB0_389:
	s_or_b64 exec, exec, s[0:1]
	s_cmpk_lt_i32 s46, 0x4000
	s_cselect_b64 s[70:71], -1, 0
	s_waitcnt lgkmcnt(0)
	v_mov_b32_e32 v0, v160
	s_and_b64 vcc, exec, s[70:71]
	v_mbcnt_lo_u32_b32 v186, -1, 0
	s_barrier
	s_cbranch_vccz .LBB0_393
	v_mbcnt_hi_u32_b32 v2, -1, v186
	v_and_b32_e32 v3, 64, v2
	v_add_u32_e32 v3, 64, v3
	s_waitcnt vmcnt(8)
	v_xor_b32_e32 v4, 1, v2
	v_cmp_lt_i32_e32 vcc, v4, v3
	s_ashr_i32 s47, s46, 31
	s_lshl_b64 s[0:1], s[46:47], 12
	v_cndmask_b32_e32 v4, v2, v4, vcc
	s_waitcnt vmcnt(5)
	v_lshlrev_b32_e32 v16, 2, v4
	v_xor_b32_e32 v4, 2, v2
	v_cmp_lt_i32_e32 vcc, v4, v3
	v_lshlrev_b32_e32 v0, 3, v0
	s_add_u32 s0, s84, s0
	v_cndmask_b32_e32 v4, v2, v4, vcc
	v_lshlrev_b32_e32 v17, 2, v4
	v_xor_b32_e32 v4, 4, v2
	v_cmp_lt_i32_e32 vcc, v4, v3
	v_ashrrev_i32_e32 v1, 31, v0
	s_addc_u32 s1, s85, s1
	v_cndmask_b32_e32 v4, v2, v4, vcc
	v_lshlrev_b32_e32 v18, 2, v4
	v_xor_b32_e32 v4, 8, v2
	v_cmp_lt_i32_e32 vcc, v4, v3
	v_lshl_add_u64 v[0:1], v[0:1], 1, s[0:1]
	s_mov_b64 s[0:1], 0x1c400000
	v_cndmask_b32_e32 v4, v2, v4, vcc
	v_lshlrev_b32_e32 v19, 2, v4
	v_xor_b32_e32 v4, 16, v2
	v_cmp_lt_i32_e32 vcc, v4, v3
	s_ashr_i32 s81, s80, 31
	v_lshl_add_u64 v[12:13], v[0:1], 0, s[0:1]
	v_cndmask_b32_e32 v4, v2, v4, vcc
	s_waitcnt vmcnt(4)
	v_lshlrev_b32_e32 v20, 2, v4
	v_xor_b32_e32 v4, 32, v2
	v_cmp_lt_i32_e32 vcc, v4, v3
	s_lshl_b64 s[20:21], s[80:81], 12
	v_mov_b32_e32 v22, 0x3727c5ac
	v_cndmask_b32_e32 v2, v2, v4, vcc
	v_lshlrev_b32_e32 v21, 2, v2
	s_mov_b32 s3, 0xf800000
	v_mov_b32_e32 v23, 0x260
	s_brev_b32 s22, 8
	s_mov_b32 s24, s46
	v_add_co_u32_e32 v232, vcc, 0xc000000, v12
	s_nop 0
	v_addc_co_u32_e32 v233, vcc, 0, v13, vcc
	global_load_dwordx4 v[200:203], v[12:13], off nt
	global_load_dwordx4 v[204:207], v[12:13], off offset:1024 nt
	global_load_dwordx4 v[208:211], v[12:13], off offset:2048 nt
	global_load_dwordx4 v[212:215], v[12:13], off offset:3072 nt
	global_load_dwordx4 v[216:219], v[232:233], off nt
	global_load_dwordx4 v[220:223], v[232:233], off offset:1024 nt
	global_load_dwordx4 v[224:227], v[232:233], off offset:2048 nt
	global_load_dwordx4 v[228:231], v[232:233], off offset:3072 nt
	s_waitcnt vmcnt(0)
.LBB0_391:
	s_waitcnt vmcnt(4)
	v_pk_mov_b32 v[0:1], v[200:201], v[200:201] op_sel:[0,1]
	v_pk_mov_b32 v[2:3], v[202:203], v[202:203] op_sel:[0,1]
	v_pk_mov_b32 v[4:5], v[204:205], v[204:205] op_sel:[0,1]
	v_pk_mov_b32 v[6:7], v[206:207], v[206:207] op_sel:[0,1]
	v_pk_mov_b32 v[8:9], v[208:209], v[208:209] op_sel:[0,1]
	v_pk_mov_b32 v[10:11], v[210:211], v[210:211] op_sel:[0,1]
	v_pk_mov_b32 v[24:25], v[212:213], v[212:213] op_sel:[0,1]
	v_pk_mov_b32 v[26:27], v[214:215], v[214:215] op_sel:[0,1]
	v_pk_mov_b32 v[28:29], v[216:217], v[216:217] op_sel:[0,1]
	v_pk_mov_b32 v[30:31], v[218:219], v[218:219] op_sel:[0,1]
	v_pk_mov_b32 v[32:33], v[220:221], v[220:221] op_sel:[0,1]
	v_pk_mov_b32 v[34:35], v[222:223], v[222:223] op_sel:[0,1]
	v_pk_mov_b32 v[36:37], v[224:225], v[224:225] op_sel:[0,1]
	v_pk_mov_b32 v[38:39], v[226:227], v[226:227] op_sel:[0,1]
	v_pk_mov_b32 v[40:41], v[228:229], v[228:229] op_sel:[0,1]
	v_pk_mov_b32 v[42:43], v[230:231], v[230:231] op_sel:[0,1]
	v_add_co_u32_e64 v14, s[0:1], s22, v12
	s_add_i32 s24, s24, s80
	s_nop 0
	v_addc_co_u32_e64 v15, s[0:1], 0, v13, s[0:1]
	v_lshl_add_u64 v[12:13], v[12:13], 0, s[20:21]
	s_cmpk_lt_i32 s24, 0x4000
	s_cbranch_scc0 .Lgn_skip
	v_add_co_u32_e32 v232, vcc, 0xc000000, v12
	s_nop 0
	v_addc_co_u32_e32 v233, vcc, 0, v13, vcc
	global_load_dwordx4 v[200:203], v[12:13], off nt
	global_load_dwordx4 v[204:207], v[12:13], off offset:1024 nt
	global_load_dwordx4 v[208:211], v[12:13], off offset:2048 nt
	global_load_dwordx4 v[212:215], v[12:13], off offset:3072 nt
	global_load_dwordx4 v[216:219], v[232:233], off nt
	global_load_dwordx4 v[220:223], v[232:233], off offset:1024 nt
	global_load_dwordx4 v[224:227], v[232:233], off offset:2048 nt
	global_load_dwordx4 v[228:231], v[232:233], off offset:3072 nt
.Lgn_skip:
	v_lshlrev_b32_e32 v44, 16, v3
	v_and_b32_e32 v45, 0xffff0000, v3
	v_lshlrev_b32_e32 v46, 16, v2
	v_and_b32_e32 v47, 0xffff0000, v2
	v_lshlrev_b32_e32 v2, 16, v1
	v_and_b32_e32 v3, 0xffff0000, v1
	v_lshlrev_b32_e32 v48, 16, v0
	v_and_b32_e32 v49, 0xffff0000, v0
	v_lshlrev_b32_e32 v0, 16, v7
	v_and_b32_e32 v1, 0xffff0000, v7
	v_lshlrev_b32_e32 v50, 16, v6
	v_and_b32_e32 v51, 0xffff0000, v6
	v_lshlrev_b32_e32 v6, 16, v5
	v_and_b32_e32 v7, 0xffff0000, v5
	v_lshlrev_b32_e32 v52, 16, v4
	v_and_b32_e32 v53, 0xffff0000, v4
	v_lshlrev_b32_e32 v4, 16, v11
	v_and_b32_e32 v5, 0xffff0000, v11
	v_lshlrev_b32_e32 v54, 16, v10
	v_and_b32_e32 v55, 0xffff0000, v10
	v_lshlrev_b32_e32 v10, 16, v9
	v_and_b32_e32 v11, 0xffff0000, v9
	v_lshlrev_b32_e32 v56, 16, v8
	v_and_b32_e32 v57, 0xffff0000, v8
	v_lshlrev_b32_e32 v8, 16, v27
	v_and_b32_e32 v9, 0xffff0000, v27
	v_lshlrev_b32_e32 v58, 16, v26
	v_and_b32_e32 v59, 0xffff0000, v26
	v_lshlrev_b32_e32 v26, 16, v25
	v_and_b32_e32 v27, 0xffff0000, v25
	v_lshlrev_b32_e32 v60, 16, v24
	v_and_b32_e32 v61, 0xffff0000, v24
	v_mul_f32_e32 v64, 0xbfb8aa3b, v46
	v_mul_f32_e32 v66, 0xbfb8aa3b, v2
	v_mul_f32_e32 v67, 0xbfb8aa3b, v3
	v_mul_f32_e32 v65, 0xbfb8aa3b, v47
	v_mul_f32_e32 v68, 0xbfb8aa3b, v48
	v_mul_f32_e32 v69, 0xbfb8aa3b, v49
	v_mul_f32_e32 v70, 0xbfb8aa3b, v44
	v_mul_f32_e32 v71, 0xbfb8aa3b, v45
	v_mul_f32_e32 v72, 0xbfb8aa3b, v50
	v_mul_f32_e32 v73, 0xbfb8aa3b, v51
	v_mul_f32_e32 v74, 0xbfb8aa3b, v6
	v_mul_f32_e32 v75, 0xbfb8aa3b, v7
	v_mul_f32_e32 v76, 0xbfb8aa3b, v52
	v_mul_f32_e32 v77, 0xbfb8aa3b, v53
	v_mul_f32_e32 v78, 0xbfb8aa3b, v0
	v_mul_f32_e32 v79, 0xbfb8aa3b, v1
	v_mul_f32_e32 v80, 0xbfb8aa3b, v54
	v_mul_f32_e32 v81, 0xbfb8aa3b, v55
	v_mul_f32_e32 v84, 0xbfb8aa3b, v56
	v_mul_f32_e32 v85, 0xbfb8aa3b, v57
	v_mul_f32_e32 v88, 0xbfb8aa3b, v58
	v_mul_f32_e32 v89, 0xbfb8aa3b, v59
	v_mul_f32_e32 v90, 0xbfb8aa3b, v26
	v_mul_f32_e32 v91, 0xbfb8aa3b, v27
	v_mul_f32_e32 v92, 0xbfb8aa3b, v60
	v_mul_f32_e32 v93, 0xbfb8aa3b, v61
	v_mul_f32_e32 v94, 0xbfb8aa3b, v8
	v_exp_f32_e32 v96, v64
	v_exp_f32_e32 v98, v66
	v_exp_f32_e32 v99, v67
	v_lshlrev_b32_e32 v64, 16, v28
	v_mul_f32_e32 v95, 0xbfb8aa3b, v9
	v_lshlrev_b32_e32 v24, 16, v31
	v_and_b32_e32 v25, 0xffff0000, v31
	v_lshlrev_b32_e32 v62, 16, v30
	v_and_b32_e32 v63, 0xffff0000, v30
	v_exp_f32_e32 v97, v65
	v_lshlrev_b32_e32 v30, 16, v29
	v_and_b32_e32 v31, 0xffff0000, v29
	v_and_b32_e32 v65, 0xffff0000, v28
	v_exp_f32_e32 v100, v68
	v_exp_f32_e32 v101, v69
	v_exp_f32_e32 v102, v70
	v_exp_f32_e32 v103, v71
	v_lshlrev_b32_e32 v28, 16, v35
	v_and_b32_e32 v29, 0xffff0000, v35
	v_lshlrev_b32_e32 v66, 16, v34
	v_and_b32_e32 v67, 0xffff0000, v34
	v_exp_f32_e32 v104, v72
	v_exp_f32_e32 v105, v73
	v_lshlrev_b32_e32 v34, 16, v33
	v_and_b32_e32 v35, 0xffff0000, v33
	v_exp_f32_e32 v106, v74
	v_exp_f32_e32 v107, v75
	v_lshlrev_b32_e32 v68, 16, v32
	v_and_b32_e32 v69, 0xffff0000, v32
	v_exp_f32_e32 v108, v76
	v_exp_f32_e32 v109, v77
	v_exp_f32_e32 v78, v78
	v_exp_f32_e32 v79, v79
	v_lshlrev_b32_e32 v32, 16, v39
	v_and_b32_e32 v33, 0xffff0000, v39
	v_lshlrev_b32_e32 v70, 16, v38
	v_and_b32_e32 v71, 0xffff0000, v38
	v_exp_f32_e32 v80, v80
	v_exp_f32_e32 v81, v81
	v_lshlrev_b32_e32 v38, 16, v37
	v_and_b32_e32 v39, 0xffff0000, v37
	v_lshlrev_b32_e32 v72, 16, v36
	v_and_b32_e32 v73, 0xffff0000, v36
	v_exp_f32_e32 v84, v84
	v_exp_f32_e32 v85, v85
	v_lshlrev_b32_e32 v36, 16, v43
	v_and_b32_e32 v37, 0xffff0000, v43
	v_lshlrev_b32_e32 v74, 16, v42
	v_and_b32_e32 v75, 0xffff0000, v42
	v_exp_f32_e32 v88, v88
	v_exp_f32_e32 v89, v89
	v_lshlrev_b32_e32 v42, 16, v41
	v_and_b32_e32 v43, 0xffff0000, v41
	v_exp_f32_e32 v41, v90
	v_exp_f32_e32 v90, v91
	v_lshlrev_b32_e32 v76, 16, v40
	v_and_b32_e32 v77, 0xffff0000, v40
	v_exp_f32_e32 v40, v92
	v_exp_f32_e32 v91, v93
	v_exp_f32_e32 v92, v94
	v_add_f32_e32 v94, 0, v64
	v_exp_f32_e32 v93, v95
	v_add_f32_e32 v95, 0, v68
	v_add_f32_e32 v110, 0, v72
	v_add_f32_e32 v111, 0, v76
	v_add_f32_e32 v94, v94, v65
	v_add_f32_e32 v95, v95, v69
	v_add_f32_e32 v110, v110, v73
	v_add_f32_e32 v111, v111, v77
	v_add_f32_e32 v94, v94, v30
	v_add_f32_e32 v95, v95, v34
	v_add_f32_e32 v110, v110, v38
	v_add_f32_e32 v111, v111, v42
	v_add_f32_e32 v98, 1.0, v98
	v_add_f32_e32 v99, 1.0, v99
	v_add_f32_e32 v94, v94, v31
	v_add_f32_e32 v96, 1.0, v96
	v_add_f32_e32 v97, 1.0, v97
	v_add_f32_e32 v100, 1.0, v100
	v_add_f32_e32 v101, 1.0, v101
	v_add_f32_e32 v104, 1.0, v104
	v_add_f32_e32 v105, 1.0, v105
	v_add_f32_e32 v108, 1.0, v108
	v_add_f32_e32 v109, 1.0, v109
	v_add_f32_e32 v95, v95, v35
	v_add_f32_e32 v112, 1.0, v78
	v_add_f32_e32 v113, 1.0, v79
	v_add_f32_e32 v114, 1.0, v80
	v_add_f32_e32 v115, 1.0, v81
	v_add_f32_e32 v118, 1.0, v84
	v_add_f32_e32 v119, 1.0, v85
	v_add_f32_e32 v110, v110, v39
	v_add_f32_e32 v122, 1.0, v88
	v_add_f32_e32 v123, 1.0, v89
	v_add_f32_e32 v126, 1.0, v40
	v_add_f32_e32 v127, 1.0, v91
	v_add_f32_e32 v111, v111, v43
	v_rcp_f32_e32 v78, v98
	v_rcp_f32_e32 v79, v99
	v_add_f32_e32 v130, v94, v62
	v_add_f32_e32 v124, 1.0, v41
	v_add_f32_e32 v128, 1.0, v92
	v_add_f32_e32 v129, 1.0, v93
	v_rcp_f32_e32 v40, v96
	v_rcp_f32_e32 v41, v97
	v_rcp_f32_e32 v80, v100
	v_rcp_f32_e32 v81, v101
	v_rcp_f32_e32 v84, v104
	v_rcp_f32_e32 v85, v105
	v_rcp_f32_e32 v88, v108
	v_rcp_f32_e32 v89, v109
	v_add_f32_e32 v108, v95, v66
	v_rcp_f32_e32 v92, v114
	v_rcp_f32_e32 v93, v115
	v_rcp_f32_e32 v96, v118
	v_rcp_f32_e32 v97, v119
	v_add_f32_e32 v109, v110, v70
	v_rcp_f32_e32 v100, v122
	v_rcp_f32_e32 v101, v123
	v_rcp_f32_e32 v104, v126
	v_rcp_f32_e32 v105, v127
	v_add_f32_e32 v110, v111, v74
	v_add_f32_e32 v111, v130, v63
	v_mul_f32_e32 v82, 0xbfb8aa3b, v10
	v_mul_f32_e32 v83, 0xbfb8aa3b, v11
	v_add_f32_e32 v108, v108, v67
	v_add_f32_e32 v109, v109, v71
	v_add_f32_e32 v110, v110, v75
	v_add_f32_e32 v111, v111, v24
	v_exp_f32_e32 v82, v82
	v_exp_f32_e32 v83, v83
	v_add_f32_e32 v108, v108, v28
	v_add_f32_e32 v109, v109, v32
	v_add_f32_e32 v110, v110, v36
	v_add_f32_e32 v111, v111, v25
	v_add_f32_e32 v108, v108, v29
	v_add_f32_e32 v109, v109, v33
	v_add_f32_e32 v110, v110, v37
	v_pk_mul_f32 v[2:3], v[78:79], v[2:3]
	ds_bpermute_b32 v78, v16, v111
	v_pk_mul_f32 v[40:41], v[40:41], v[46:47]
	v_pk_mul_f32 v[46:47], v[80:81], v[48:49]
	v_pk_mul_f32 v[48:49], v[84:85], v[50:51]
	v_pk_mul_f32 v[50:51], v[88:89], v[52:53]
	ds_bpermute_b32 v79, v16, v108
	v_pk_mul_f32 v[52:53], v[92:93], v[54:55]
	v_pk_mul_f32 v[54:55], v[96:97], v[56:57]
	ds_bpermute_b32 v80, v16, v109
	v_pk_mul_f32 v[56:57], v[100:101], v[58:59]
	v_pk_mul_f32 v[58:59], v[104:105], v[60:61]
	ds_bpermute_b32 v60, v16, v110
	v_add_f32_e32 v102, 1.0, v102
	v_add_f32_e32 v103, 1.0, v103
	v_add_f32_e32 v116, 1.0, v82
	v_add_f32_e32 v117, 1.0, v83
	v_rcp_f32_e32 v82, v102
	v_rcp_f32_e32 v83, v103
	s_waitcnt lgkmcnt(3)
	v_add_f32_e32 v61, v111, v78
	s_waitcnt lgkmcnt(2)
	v_add_f32_e32 v78, v108, v79
	s_waitcnt lgkmcnt(1)
	v_add_f32_e32 v79, v109, v80
	s_waitcnt lgkmcnt(0)
	v_add_f32_e32 v60, v110, v60
	ds_bpermute_b32 v80, v17, v61
	v_pk_mul_f32 v[44:45], v[82:83], v[44:45]
	ds_bpermute_b32 v81, v17, v78
	ds_bpermute_b32 v82, v17, v79
	ds_bpermute_b32 v83, v17, v60
	s_waitcnt lgkmcnt(3)
	v_add_f32_e32 v61, v61, v80
	ds_bpermute_b32 v80, v18, v61
	s_waitcnt lgkmcnt(3)
	v_add_f32_e32 v78, v78, v81
	s_waitcnt lgkmcnt(2)
	v_add_f32_e32 v79, v79, v82
	s_waitcnt lgkmcnt(1)
	v_add_f32_e32 v60, v60, v83
	ds_bpermute_b32 v81, v18, v78
	ds_bpermute_b32 v82, v18, v79
	ds_bpermute_b32 v83, v18, v60
	s_waitcnt lgkmcnt(3)
	v_add_f32_e32 v61, v61, v80
	ds_bpermute_b32 v80, v19, v61
	s_waitcnt lgkmcnt(3)
	v_add_f32_e32 v78, v78, v81
	s_waitcnt lgkmcnt(2)
	v_add_f32_e32 v79, v79, v82
	s_waitcnt lgkmcnt(1)
	v_add_f32_e32 v60, v60, v83
	ds_bpermute_b32 v81, v19, v78
	ds_bpermute_b32 v82, v19, v79
	ds_bpermute_b32 v83, v19, v60
	s_waitcnt lgkmcnt(3)
	v_add_f32_e32 v61, v61, v80
	ds_bpermute_b32 v80, v20, v61
	s_waitcnt lgkmcnt(3)
	v_add_f32_e32 v78, v78, v81
	s_waitcnt lgkmcnt(2)
	v_add_f32_e32 v79, v79, v82
	s_waitcnt lgkmcnt(1)
	v_add_f32_e32 v60, v60, v83
	ds_bpermute_b32 v81, v20, v78
	ds_bpermute_b32 v82, v20, v79
	ds_bpermute_b32 v83, v20, v60
	v_mul_f32_e32 v86, 0xbfb8aa3b, v4
	v_mul_f32_e32 v87, 0xbfb8aa3b, v5
	v_exp_f32_e32 v86, v86
	v_exp_f32_e32 v87, v87
	s_waitcnt lgkmcnt(3)
	v_add_f32_e32 v61, v61, v80
	s_waitcnt lgkmcnt(2)
	v_add_f32_e32 v78, v78, v81
	s_waitcnt lgkmcnt(1)
	v_add_f32_e32 v79, v79, v82
	s_waitcnt lgkmcnt(0)
	v_add_f32_e32 v60, v60, v83
	ds_bpermute_b32 v80, v21, v61
	ds_bpermute_b32 v81, v21, v78
	ds_bpermute_b32 v82, v21, v79
	ds_bpermute_b32 v83, v21, v60
	v_add_f32_e32 v106, 1.0, v106
	v_add_f32_e32 v107, 1.0, v107
	v_add_f32_e32 v120, 1.0, v86
	v_add_f32_e32 v121, 1.0, v87
	v_add_f32_e32 v125, 1.0, v90
	v_rcp_f32_e32 v86, v106
	v_rcp_f32_e32 v87, v107
	v_rcp_f32_e32 v90, v112
	v_rcp_f32_e32 v91, v113
	v_rcp_f32_e32 v94, v116
	v_rcp_f32_e32 v95, v117
	v_rcp_f32_e32 v98, v120
	v_rcp_f32_e32 v99, v121
	v_rcp_f32_e32 v106, v128
	v_rcp_f32_e32 v107, v129
	s_waitcnt lgkmcnt(3)
	v_add_f32_e32 v61, v61, v80
	s_waitcnt lgkmcnt(2)
	v_add_f32_e32 v78, v78, v81
	s_waitcnt lgkmcnt(1)
	v_add_f32_e32 v79, v79, v82
	s_waitcnt lgkmcnt(0)
	v_add_f32_e32 v81, v60, v83
	v_mul_f32_e32 v60, 0x3b000000, v61
	v_mul_f32_e32 v78, 0x3b000000, v78
	v_mul_f32_e32 v80, 0x3b000000, v79
	v_mul_f32_e32 v82, 0x3b000000, v81
	v_pk_add_f32 v[64:65], v[64:65], v[60:61] op_sel_hi:[1,0] neg_lo:[0,1] neg_hi:[0,1]
	v_pk_mul_f32 v[6:7], v[86:87], v[6:7]
	v_pk_mul_f32 v[0:1], v[90:91], v[0:1]
	v_pk_mul_f32 v[10:11], v[94:95], v[10:11]
	v_pk_mul_f32 v[4:5], v[98:99], v[4:5]
	v_pk_mul_f32 v[8:9], v[106:107], v[8:9]
	v_pk_add_f32 v[30:31], v[30:31], v[60:61] op_sel_hi:[1,0] neg_lo:[0,1] neg_hi:[0,1]
	v_pk_add_f32 v[62:63], v[62:63], v[60:61] op_sel_hi:[1,0] neg_lo:[0,1] neg_hi:[0,1]
	v_pk_add_f32 v[24:25], v[24:25], v[60:61] op_sel_hi:[1,0] neg_lo:[0,1] neg_hi:[0,1]
	v_pk_add_f32 v[60:61], v[68:69], v[78:79] op_sel_hi:[1,0] neg_lo:[0,1] neg_hi:[0,1]
	v_pk_add_f32 v[34:35], v[34:35], v[78:79] op_sel_hi:[1,0] neg_lo:[0,1] neg_hi:[0,1]
	v_pk_add_f32 v[66:67], v[66:67], v[78:79] op_sel_hi:[1,0] neg_lo:[0,1] neg_hi:[0,1]
	v_pk_add_f32 v[28:29], v[28:29], v[78:79] op_sel_hi:[1,0] neg_lo:[0,1] neg_hi:[0,1]
	v_pk_add_f32 v[68:69], v[72:73], v[80:81] op_sel_hi:[1,0] neg_lo:[0,1] neg_hi:[0,1]
	v_pk_add_f32 v[38:39], v[38:39], v[80:81] op_sel_hi:[1,0] neg_lo:[0,1] neg_hi:[0,1]
	v_pk_add_f32 v[70:71], v[70:71], v[80:81] op_sel_hi:[1,0] neg_lo:[0,1] neg_hi:[0,1]
	v_pk_add_f32 v[32:33], v[32:33], v[80:81] op_sel_hi:[1,0] neg_lo:[0,1] neg_hi:[0,1]
	v_pk_add_f32 v[72:73], v[76:77], v[82:83] op_sel_hi:[1,0] neg_lo:[0,1] neg_hi:[0,1]
	v_pk_add_f32 v[36:37], v[36:37], v[82:83] op_sel_hi:[1,0] neg_lo:[0,1] neg_hi:[0,1]
	v_pk_mul_f32 v[76:77], v[64:65], v[64:65]
	v_pk_add_f32 v[42:43], v[42:43], v[82:83] op_sel_hi:[1,0] neg_lo:[0,1] neg_hi:[0,1]
	v_pk_add_f32 v[74:75], v[74:75], v[82:83] op_sel_hi:[1,0] neg_lo:[0,1] neg_hi:[0,1]
	v_pk_mul_f32 v[78:79], v[30:31], v[30:31]
	v_pk_mul_f32 v[80:81], v[62:63], v[62:63]
	v_pk_mul_f32 v[82:83], v[24:25], v[24:25]
	v_pk_mul_f32 v[46:47], v[46:47], v[64:65]
	v_pk_mul_f32 v[2:3], v[2:3], v[30:31]
	v_pk_mul_f32 v[30:31], v[40:41], v[62:63]
	v_pk_mul_f32 v[24:25], v[44:45], v[24:25]
	v_pk_mul_f32 v[40:41], v[60:61], v[60:61]
	v_pk_mul_f32 v[44:45], v[34:35], v[34:35]
	v_pk_mul_f32 v[62:63], v[66:67], v[66:67]
	v_pk_mul_f32 v[64:65], v[28:29], v[28:29]
	v_pk_mul_f32 v[50:51], v[50:51], v[60:61]
	v_pk_mul_f32 v[6:7], v[6:7], v[34:35]
	v_pk_mul_f32 v[34:35], v[48:49], v[66:67]
	v_pk_mul_f32 v[28:29], v[0:1], v[28:29]
	v_pk_mul_f32 v[0:1], v[68:69], v[68:69]
	v_pk_mul_f32 v[48:49], v[38:39], v[38:39]
	v_pk_mul_f32 v[60:61], v[70:71], v[70:71]
	v_pk_mul_f32 v[66:67], v[32:33], v[32:33]
	v_pk_mul_f32 v[10:11], v[10:11], v[38:39]
	v_pk_mul_f32 v[38:39], v[52:53], v[70:71]
	v_pk_mul_f32 v[4:5], v[4:5], v[32:33]
	v_pk_mul_f32 v[32:33], v[72:73], v[72:73]
	v_pk_mul_f32 v[70:71], v[36:37], v[36:37]
	v_pk_mul_f32 v[8:9], v[8:9], v[36:37]
	v_add_f32_e32 v36, v76, v77
	v_add_f32_e32 v37, v40, v41
	v_add_f32_e32 v0, v0, v1
	v_add_f32_e32 v1, v32, v33
	v_add_f32_e32 v32, v78, v36
	v_add_f32_e32 v33, v44, v37
	v_add_f32_e32 v0, v48, v0
	v_add_f32_e32 v32, v79, v32
	v_pk_mul_f32 v[52:53], v[42:43], v[42:43]
	v_add_f32_e32 v33, v45, v33
	v_add_f32_e32 v0, v49, v0
	v_add_f32_e32 v32, v80, v32
	v_add_f32_e32 v1, v52, v1
	v_add_f32_e32 v33, v62, v33
	v_add_f32_e32 v0, v60, v0
	v_add_f32_e32 v32, v81, v32
	v_pk_mul_f32 v[54:55], v[54:55], v[68:69]
	v_pk_mul_f32 v[68:69], v[74:75], v[74:75]
	v_add_f32_e32 v1, v53, v1
	v_add_f32_e32 v33, v63, v33
	v_add_f32_e32 v0, v61, v0
	v_add_f32_e32 v32, v82, v32
	v_add_f32_e32 v1, v68, v1
	v_add_f32_e32 v33, v64, v33
	v_add_f32_e32 v0, v66, v0
	v_add_f32_e32 v32, v83, v32
	v_add_f32_e32 v1, v69, v1
	v_add_f32_e32 v33, v65, v33
	v_add_f32_e32 v0, v67, v0
	ds_bpermute_b32 v36, v16, v32
	v_add_f32_e32 v1, v70, v1
	ds_bpermute_b32 v37, v16, v33
	ds_bpermute_b32 v40, v16, v0
	v_add_f32_e32 v1, v71, v1
	ds_bpermute_b32 v41, v16, v1
	s_waitcnt lgkmcnt(3)
	v_add_f32_e32 v32, v32, v36
	s_waitcnt lgkmcnt(2)
	v_add_f32_e32 v33, v33, v37
	s_waitcnt lgkmcnt(1)
	v_add_f32_e32 v0, v0, v40
	ds_bpermute_b32 v36, v17, v32
	ds_bpermute_b32 v37, v17, v33
	ds_bpermute_b32 v40, v17, v0
	s_waitcnt lgkmcnt(3)
	v_add_f32_e32 v1, v1, v41
	ds_bpermute_b32 v41, v17, v1
	s_waitcnt lgkmcnt(3)
	v_add_f32_e32 v32, v32, v36
	s_waitcnt lgkmcnt(2)
	v_add_f32_e32 v33, v33, v37
	s_waitcnt lgkmcnt(1)
	v_add_f32_e32 v0, v0, v40
	ds_bpermute_b32 v36, v18, v32
	ds_bpermute_b32 v37, v18, v33
	ds_bpermute_b32 v40, v18, v0
	s_waitcnt lgkmcnt(3)
	v_add_f32_e32 v1, v1, v41
	ds_bpermute_b32 v41, v18, v1
	s_waitcnt lgkmcnt(3)
	v_add_f32_e32 v32, v32, v36
	s_waitcnt lgkmcnt(2)
	v_add_f32_e32 v33, v33, v37
	s_waitcnt lgkmcnt(1)
	v_add_f32_e32 v0, v0, v40
	ds_bpermute_b32 v36, v19, v32
	ds_bpermute_b32 v37, v19, v33
	ds_bpermute_b32 v40, v19, v0
	s_waitcnt lgkmcnt(3)
	v_add_f32_e32 v1, v1, v41
	ds_bpermute_b32 v41, v19, v1
	s_waitcnt lgkmcnt(3)
	v_add_f32_e32 v32, v32, v36
	s_waitcnt lgkmcnt(2)
	v_add_f32_e32 v33, v33, v37
	s_waitcnt lgkmcnt(1)
	v_add_f32_e32 v0, v0, v40
	ds_bpermute_b32 v36, v20, v32
	ds_bpermute_b32 v37, v20, v33
	ds_bpermute_b32 v40, v20, v0
	s_waitcnt lgkmcnt(3)
	v_add_f32_e32 v1, v1, v41
	ds_bpermute_b32 v41, v20, v1
	s_waitcnt lgkmcnt(3)
	v_add_f32_e32 v32, v32, v36
	s_waitcnt lgkmcnt(2)
	v_add_f32_e32 v33, v33, v37
	s_waitcnt lgkmcnt(1)
	v_add_f32_e32 v0, v0, v40
	ds_bpermute_b32 v36, v21, v32
	ds_bpermute_b32 v37, v21, v33
	ds_bpermute_b32 v40, v21, v0
	s_waitcnt lgkmcnt(3)
	v_add_f32_e32 v1, v1, v41
	ds_bpermute_b32 v41, v21, v1
	s_waitcnt lgkmcnt(3)
	v_add_f32_e32 v32, v32, v36
	s_waitcnt lgkmcnt(2)
	v_add_f32_e32 v33, v33, v37
	s_waitcnt lgkmcnt(1)
	v_add_f32_e32 v0, v0, v40
	v_fmamk_f32 v32, v32, 0x3b000000, v22
	v_fmamk_f32 v33, v33, 0x3b000000, v22
	v_fmamk_f32 v0, v0, 0x3b000000, v22
	v_mul_f32_e32 v36, 0x4f800000, v32
	v_cmp_gt_f32_e64 s[6:7], s3, v32
	s_waitcnt lgkmcnt(0)
	v_add_f32_e32 v1, v1, v41
	v_mul_f32_e32 v37, 0x4f800000, v33
	v_cmp_gt_f32_e32 vcc, s3, v33
	v_mul_f32_e32 v40, 0x4f800000, v0
	v_cmp_gt_f32_e64 s[0:1], s3, v0
	v_cndmask_b32_e64 v32, v32, v36, s[6:7]
	v_fmamk_f32 v1, v1, 0x3b000000, v22
	v_cndmask_b32_e32 v33, v33, v37, vcc
	v_cndmask_b32_e64 v0, v0, v40, s[0:1]
	v_sqrt_f32_e32 v36, v32
	v_mul_f32_e32 v41, 0x4f800000, v1
	v_cmp_gt_f32_e64 s[4:5], s3, v1
	v_sqrt_f32_e32 v37, v33
	v_sqrt_f32_e32 v40, v0
	v_rcp_f32_e32 v102, v124
	v_rcp_f32_e32 v103, v125
	v_cndmask_b32_e64 v1, v1, v41, s[4:5]
	v_sqrt_f32_e32 v41, v1
	v_add_u32_e32 v44, -1, v36
	v_add_u32_e32 v45, 1, v36
	v_add_u32_e32 v48, -1, v37
	v_add_u32_e32 v52, -1, v40
	v_fma_f32 v60, -v44, v36, v32
	v_pk_mul_f32 v[26:27], v[102:103], v[26:27]
	v_add_u32_e32 v49, 1, v37
	v_add_u32_e32 v53, 1, v40
	v_fma_f32 v61, -v45, v36, v32
	v_fma_f32 v62, -v48, v37, v33
	v_fma_f32 v64, -v52, v40, v0
	v_cmp_ge_f32_e64 s[8:9], 0, v60
	v_pk_mul_f32 v[26:27], v[26:27], v[42:43]
	v_pk_mul_f32 v[42:43], v[56:57], v[74:75]
	v_add_u32_e32 v56, -1, v41
	v_fma_f32 v63, -v49, v37, v33
	v_fma_f32 v65, -v53, v40, v0
	v_cndmask_b32_e64 v36, v36, v44, s[8:9]
	v_cmp_ge_f32_e64 s[8:9], 0, v62
	v_cmp_ge_f32_e64 s[10:11], 0, v64
	v_cmp_lt_f32_e64 s[14:15], 0, v61
	v_add_u32_e32 v57, 1, v41
	v_fma_f32 v66, -v56, v41, v1
	v_cndmask_b32_e64 v37, v37, v48, s[8:9]
	v_cmp_lt_f32_e64 s[8:9], 0, v63
	v_cndmask_b32_e64 v40, v40, v52, s[10:11]
	v_cmp_lt_f32_e64 s[10:11], 0, v65
	v_cndmask_b32_e64 v36, v36, v45, s[14:15]
	v_fma_f32 v67, -v57, v41, v1
	v_cmp_ge_f32_e64 s[12:13], 0, v66
	v_cndmask_b32_e64 v37, v37, v49, s[8:9]
	v_cndmask_b32_e64 v40, v40, v53, s[10:11]
	v_mul_f32_e32 v44, 0x37800000, v36
	v_cndmask_b32_e64 v41, v41, v56, s[12:13]
	v_cmp_lt_f32_e64 s[12:13], 0, v67
	v_mul_f32_e32 v45, 0x37800000, v37
	v_mul_f32_e32 v48, 0x37800000, v40
	v_cndmask_b32_e64 v36, v36, v44, s[6:7]
	v_cmp_class_f32_e64 s[6:7], v32, v23
	v_cndmask_b32_e64 v41, v41, v57, s[12:13]
	v_cndmask_b32_e32 v37, v37, v45, vcc
	v_cmp_class_f32_e32 vcc, v33, v23
	v_cndmask_b32_e64 v40, v40, v48, s[0:1]
	v_cmp_class_f32_e64 s[0:1], v0, v23
	v_cndmask_b32_e64 v32, v36, v32, s[6:7]
	v_mul_f32_e32 v49, 0x37800000, v41
	v_cndmask_b32_e32 v36, v37, v33, vcc
	v_cndmask_b32_e64 v37, v40, v0, s[0:1]
	v_div_scale_f32 v0, s[0:1], v32, v32, 1.0
	v_cndmask_b32_e64 v41, v41, v49, s[4:5]
	v_cmp_class_f32_e64 s[4:5], v1, v23
	v_div_scale_f32 v33, s[0:1], v36, v36, 1.0
	v_rcp_f32_e32 v52, v0
	v_cndmask_b32_e64 v40, v41, v1, s[4:5]
	v_div_scale_f32 v44, s[4:5], v37, v37, 1.0
	v_rcp_f32_e32 v53, v33
	v_div_scale_f32 v48, s[6:7], v40, v40, 1.0
	v_rcp_f32_e32 v56, v44
	v_rcp_f32_e32 v57, v48
	v_fma_f32 v60, -v0, v52, 1.0
	v_div_scale_f32 v1, vcc, 1.0, v32, 1.0
	v_fma_f32 v61, -v33, v53, 1.0
	v_fmac_f32_e32 v52, v60, v52
	v_div_scale_f32 v41, s[0:1], 1.0, v36, 1.0
	v_fma_f32 v62, -v44, v56, 1.0
	v_fmac_f32_e32 v53, v61, v53
	v_mul_f32_e32 v60, v1, v52
	v_div_scale_f32 v45, s[4:5], 1.0, v37, 1.0
	v_fma_f32 v63, -v48, v57, 1.0
	v_fmac_f32_e32 v56, v62, v56
	v_mul_f32_e32 v61, v41, v53
	v_fma_f32 v64, -v0, v60, v1
	v_div_scale_f32 v49, s[6:7], 1.0, v40, 1.0
	v_fmac_f32_e32 v57, v63, v57
	v_mul_f32_e32 v62, v45, v56
	v_fma_f32 v65, -v33, v61, v41
	v_fmac_f32_e32 v60, v64, v52
	v_mul_f32_e32 v63, v49, v57
	v_fma_f32 v66, -v44, v62, v45
	v_fmac_f32_e32 v61, v65, v53
	v_fma_f32 v0, -v0, v60, v1
	v_fma_f32 v67, -v48, v63, v49
	v_fmac_f32_e32 v62, v66, v56
	v_fma_f32 v1, -v33, v61, v41
	v_div_fmas_f32 v0, v0, v52, v60
	s_mov_b64 vcc, s[0:1]
	v_fmac_f32_e32 v63, v67, v57
	v_fma_f32 v41, -v44, v62, v45
	v_div_fixup_f32 v0, v0, v32, 1.0
	v_div_fmas_f32 v1, v1, v53, v61
	s_mov_b64 vcc, s[4:5]
	v_fma_f32 v44, -v48, v63, v49
	v_pk_mul_f32 v[32:33], v[46:47], v[0:1] op_sel_hi:[1,0]
	v_pk_mul_f32 v[2:3], v[2:3], v[0:1] op_sel_hi:[1,0]
	v_pk_mul_f32 v[30:31], v[30:31], v[0:1] op_sel_hi:[1,0]
	v_pk_mul_f32 v[24:25], v[24:25], v[0:1] op_sel_hi:[1,0]
	v_div_fixup_f32 v36, v1, v36, 1.0
	v_div_fmas_f32 v41, v41, v56, v62
	s_mov_b64 vcc, s[6:7]
	v_cvt_pk_bf16_f32 v0, v32, v33
	v_cvt_pk_bf16_f32 v1, v2, v3
	v_cvt_pk_bf16_f32 v2, v30, v31
	v_cvt_pk_bf16_f32 v3, v24, v25
	v_pk_mul_f32 v[24:25], v[50:51], v[36:37] op_sel_hi:[1,0]
	v_pk_mul_f32 v[6:7], v[6:7], v[36:37] op_sel_hi:[1,0]
	v_pk_mul_f32 v[30:31], v[34:35], v[36:37] op_sel_hi:[1,0]
	v_pk_mul_f32 v[28:29], v[28:29], v[36:37] op_sel_hi:[1,0]
	v_div_fixup_f32 v32, v41, v37, 1.0
	v_div_fmas_f32 v33, v44, v57, v63
	v_pk_mul_f32 v[58:59], v[58:59], v[72:73]
	global_store_dwordx4 v[14:15], v[0:3], off
	v_pk_mul_f32 v[10:11], v[10:11], v[32:33] op_sel_hi:[1,0]
	v_pk_mul_f32 v[4:5], v[4:5], v[32:33] op_sel_hi:[1,0]
	v_cvt_pk_bf16_f32 v0, v24, v25
	v_cvt_pk_bf16_f32 v1, v6, v7
	v_cvt_pk_bf16_f32 v2, v30, v31
	v_cvt_pk_bf16_f32 v3, v28, v29
	v_pk_mul_f32 v[6:7], v[54:55], v[32:33] op_sel_hi:[1,0]
	v_pk_mul_f32 v[24:25], v[38:39], v[32:33] op_sel_hi:[1,0]
	v_div_fixup_f32 v28, v33, v40, 1.0
	global_store_dwordx4 v[14:15], v[0:3], off offset:1024
	v_pk_mul_f32 v[8:9], v[8:9], v[28:29] op_sel_hi:[1,0]
	s_nop 0
	v_cvt_pk_bf16_f32 v0, v6, v7
	v_cvt_pk_bf16_f32 v1, v10, v11
	v_cvt_pk_bf16_f32 v2, v24, v25
	v_cvt_pk_bf16_f32 v3, v4, v5
	v_pk_mul_f32 v[4:5], v[58:59], v[28:29] op_sel_hi:[1,0]
	v_pk_mul_f32 v[6:7], v[26:27], v[28:29] op_sel_hi:[1,0]
	v_pk_mul_f32 v[10:11], v[42:43], v[28:29] op_sel_hi:[1,0]
	global_store_dwordx4 v[14:15], v[0:3], off offset:2048
	s_nop 1
	v_cvt_pk_bf16_f32 v0, v4, v5
	v_cvt_pk_bf16_f32 v1, v6, v7
	v_cvt_pk_bf16_f32 v2, v10, v11
	v_cvt_pk_bf16_f32 v3, v8, v9
	global_store_dwordx4 v[14:15], v[0:3], off offset:3072
	s_cbranch_scc1 .LBB0_391
	v_readlane_b32 s81, v234, 49
